# FFN-in SwiGLU epilogue: the per-row-block sum-of-squares loads are issued together up front instead of one serialized load+wait per block
# speedup vs baseline: 1.0529x; 1.0035x over previous
; __device__ __forceinline__ unsigned cvt_pk_bf16(float lo, float hi) { const f32x2 v = {lo, hi}; return __builtin_bit_cast(unsigned, __builtin_convertvector(v, bf16x2_t)); }
; __device__ __forceinline__ float fast_silu(float g) { return g * __builtin_amdgcn_rcpf(1.0f + __builtin_amdgcn_exp2f(-1.4426950408889634f * g)); }
; __device__ __forceinline__ float sum4(f32x4 v) { return (v.x + v.y) + (v.z + v.w); }
; __device__ __forceinline__ float quad_sum(float t, int lane) { t += shx(t, 16, lane); t += shx(t, 32, lane); return t; }
;     template <int A0, int A1> __device__ __forceinline__ void run(const f32x4 (&acc)[2][2][4][2], const Unit& u, int wr, int wc, int fr, int fq) const {
;         const int s = stream_of(u.pm);
;         const int cb = u.pn * 256 + wc * 32 + fq * 8;
;         const float* bp = sW + s * NFF + cb;
;         f32x4 bg[2], bu[2];
; #pragma unroll
;         for (int n = 0; n < 2; ++n) { bg[n] = *(const f32x4*)(bp + 4 * n); bu[n] = *(const f32x4*)(bp + 128 + 4 * n); }
;         const int row0 = u.pm * 256 + wr * 64 + fr;
; #pragma unroll
;         for (int ai = A0; ai < A1; ++ai)
; #pragma unroll
;             for (int m = 0; m < 4; ++m) {
;                 const int row = row0 + ai * 128 + m * 16;
;                 const float t = quad_sum(sum4(*(const f32x4*)(ssqp + (size_t)row * 16 + 4 * fq)), fq * 16 + fr);
;                 const float rr = rsqrtf(t * (1.0f / 1024.0f) + EPS);
;                 u32x4 w;
; #pragma unroll
;                 for (int n = 0; n < 2; ++n) {
;                     const f32x4 gg = acc[ai][0][m][n] * rr + bg[n], uu = acc[ai][1][m][n] * rr + bu[n];
;                     const float h0 = fast_silu(gg.x) * uu.x, h1 = fast_silu(gg.y) * uu.y, h2 = fast_silu(gg.z) * uu.z, h3 = fast_silu(gg.w) * uu.w;
;                     w[2 * n] = cvt_pk_bf16(h0, h1); w[2 * n + 1] = cvt_pk_bf16(h2, h3);
;                 }
;                 bf16_t* hp = H + (size_t)row * DFF + u.pn * 128 + wc * 32 + fq * 8;
;                 if (cnt) asm volatile("global_store_dwordx4 %0, %1, off sc0 sc1" :: "v"(hp), "v"(w) : "memory");
;                 else *(u32x4*)hp = w;
;             }
.LBB0_235:
	s_cmp_lt_u32 s16, 64
	s_cselect_b32 s7, s1, 0x2c00
	s_cmp_gt_i32 s16, 31
	s_cselect_b32 s7, s7, 0
	s_lshl_b32 s7, s7, 2
	v_lshl_add_u32 v160, s16, 8, v162
	v_lshl_or_b32 v32, s6, 8, v166
	s_add_u32 s20, s67, s7
	v_ashrrev_i32_e32 v161, 31, v160
	s_addc_u32 s21, s87, 0
	v_ashrrev_i32_e32 v33, 31, v32
	v_lshlrev_b64 v[168:169], 6, v[160:161]
	v_lshl_add_u64 v[40:41], v[32:33], 2, s[20:21]
	v_lshl_add_u64 v[168:169], v[154:155], 0, v[168:169]
	global_load_dwordx4 v[36:39], v[40:41], off offset:16
	global_load_dwordx4 v[44:47], v[40:41], off
	global_load_dwordx4 v[32:35], v[40:41], off offset:528
	s_nop 0
	global_load_dwordx4 v[40:43], v[40:41], off offset:512
	s_lshl_b32 s84, s6, 7
	global_load_dwordx4 v[224:227], v[168:169], off offset:1024
	global_load_dwordx4 v[228:231], v[168:169], off offset:2048
	global_load_dwordx4 v[232:235], v[168:169], off offset:3072
	v_mov_b32_e32 v236, 0x2000
	v_mov_b32_e32 v237, 0
	v_lshl_add_u64 v[236:237], v[168:169], 0, v[236:237]
	global_load_dwordx4 v[240:243], v[236:237], off
	global_load_dwordx4 v[244:247], v[236:237], off offset:1024
	global_load_dwordx4 v[248:251], v[236:237], off offset:2048
	global_load_dwordx4 v[168:171], v[168:169], off
	s_ashr_i32 s85, s84, 31
	s_waitcnt vmcnt(0)
	v_mov_b32_e32 v172, v169
	v_mov_b32_e32 v173, v170
	v_mov_b32_e32 v169, v171
	v_pk_add_f32 v[168:169], v[172:173], v[168:169]
	s_nop 0
	v_add_f32_e32 v161, v168, v169
	ds_bpermute_b32 v168, v164, v161
	s_waitcnt lgkmcnt(0)
	v_add_f32_e32 v161, v161, v168
	ds_bpermute_b32 v168, v165, v161
	s_waitcnt lgkmcnt(0)
	v_add_f32_e32 v161, v161, v168
	v_fmamk_f32 v161, v161, 0x3a800000, v252
	v_cmp_gt_f32_e32 vcc, s49, v161
	v_mul_f32_e32 v168, 0x4b800000, v161
	s_nop 0
	v_cndmask_b32_e32 v161, v161, v168, vcc
	v_rsq_f32_e32 v161, v161
	s_nop 0
	v_mul_f32_e32 v168, 0x45800000, v161
	v_cndmask_b32_e32 v168, v161, v168, vcc
	v_pk_fma_f32 v[142:143], v[142:143], v[168:169], v[44:45] op_sel_hi:[1,0,1]
	v_pk_fma_f32 v[144:145], v[144:145], v[168:169], v[46:47] op_sel_hi:[1,0,1]
	v_mul_f32_e32 v161, 0xbfb8aa3b, v142
	v_exp_f32_e32 v161, v161
	v_pk_fma_f32 v[134:135], v[134:135], v[168:169], v[40:41] op_sel_hi:[1,0,1]
	v_pk_fma_f32 v[136:137], v[136:137], v[168:169], v[42:43] op_sel_hi:[1,0,1]
	v_pk_fma_f32 v[138:139], v[138:139], v[168:169], v[36:37] op_sel_hi:[1,0,1]
	v_add_f32_e32 v161, 1.0, v161
	v_rcp_f32_e32 v170, v161
	v_mul_f32_e32 v161, 0xbfb8aa3b, v143
	v_exp_f32_e32 v161, v161
	v_pk_fma_f32 v[130:131], v[130:131], v[168:169], v[32:33] op_sel_hi:[1,0,1]
	v_pk_fma_f32 v[132:133], v[132:133], v[168:169], v[34:35] op_sel_hi:[1,0,1]
	s_andn2_b64 vcc, exec, s[24:25]
	v_add_f32_e32 v161, 1.0, v161
	v_rcp_f32_e32 v171, v161
	s_nop 0
	v_pk_mul_f32 v[142:143], v[142:143], v[170:171]
	s_nop 0
	v_pk_mul_f32 v[134:135], v[134:135], v[142:143]
	v_mul_f32_e32 v142, 0xbfb8aa3b, v144
	v_mul_f32_e32 v143, 0xbfb8aa3b, v145
	v_exp_f32_e32 v142, v142
	v_exp_f32_e32 v143, v143
	v_cvt_pk_bf16_f32 v134, v134, v135
	v_add_f32_e32 v142, 1.0, v142
	v_add_f32_e32 v143, 1.0, v143
	v_rcp_f32_e32 v142, v142
	v_rcp_f32_e32 v143, v143
	s_nop 0
	v_pk_mul_f32 v[142:143], v[144:145], v[142:143]
	s_nop 0
	v_pk_mul_f32 v[136:137], v[136:137], v[142:143]
	s_nop 0
	v_cvt_pk_bf16_f32 v135, v136, v137
	v_pk_fma_f32 v[136:137], v[140:141], v[168:169], v[38:39] op_sel_hi:[1,0,1]
	v_mul_f32_e32 v140, 0xbfb8aa3b, v138
	v_mul_f32_e32 v141, 0xbfb8aa3b, v139
	v_exp_f32_e32 v140, v140
	v_exp_f32_e32 v141, v141
	v_add_f32_e32 v140, 1.0, v140
	v_add_f32_e32 v141, 1.0, v141
	v_rcp_f32_e32 v140, v140
	v_rcp_f32_e32 v141, v141
	s_nop 0
	v_pk_mul_f32 v[138:139], v[138:139], v[140:141]
	s_nop 0
	v_pk_mul_f32 v[130:131], v[130:131], v[138:139]
	v_mul_f32_e32 v138, 0xbfb8aa3b, v136
	v_mul_f32_e32 v139, 0xbfb8aa3b, v137
	v_exp_f32_e32 v138, v138
	v_exp_f32_e32 v139, v139
	v_add_f32_e32 v138, 1.0, v138
	v_add_f32_e32 v139, 1.0, v139
	v_rcp_f32_e32 v138, v138
	v_rcp_f32_e32 v139, v139
	s_nop 0
	v_pk_mul_f32 v[136:137], v[136:137], v[138:139]
	s_nop 0
	v_pk_mul_f32 v[132:133], v[132:133], v[136:137]
	v_cvt_pk_bf16_f32 v136, v130, v131
	v_mov_b64_e32 v[130:131], s[12:13]
	v_mad_i64_i32 v[130:131], s[20:21], v160, s1, v[130:131]
	v_lshl_add_u64 v[130:131], s[84:85], 1, v[130:131]
	v_cvt_pk_bf16_f32 v137, v132, v133
	v_lshl_add_u64 v[130:131], v[130:131], 0, s[52:53]
	v_cndmask_b32_e64 v132, 0, 1, s[24:25]
	v_lshl_add_u64 v[130:131], v[130:131], 0, v[128:129]
	v_cmp_ne_u32_e64 s[6:7], 1, v132
	s_cbranch_vccnz .LBB0_267
	global_store_dwordx4 v[130:131], v[134:137], off sc0 sc1
	s_cbranch_execnz .LBB0_238

; __device__ __forceinline__ unsigned cvt_pk_bf16(float lo, float hi) { const f32x2 v = {lo, hi}; return __builtin_bit_cast(unsigned, __builtin_convertvector(v, bf16x2_t)); }
; __device__ __forceinline__ float fast_silu(float g) { return g * __builtin_amdgcn_rcpf(1.0f + __builtin_amdgcn_exp2f(-1.4426950408889634f * g)); }
; __device__ __forceinline__ float sum4(f32x4 v) { return (v.x + v.y) + (v.z + v.w); }
; __device__ __forceinline__ float quad_sum(float t, int lane) { t += shx(t, 16, lane); t += shx(t, 32, lane); return t; }
;     template <int A0, int A1> __device__ __forceinline__ void run(const f32x4 (&acc)[2][2][4][2], const Unit& u, int wr, int wc, int fr, int fq) const {
;     ...
;             for (int m = 0; m < 4; ++m) {
;                 const int row = row0 + ai * 128 + m * 16;
;                 const float t = quad_sum(sum4(*(const f32x4*)(ssqp + (size_t)row * 16 + 4 * fq)), fq * 16 + fr);
;                 const float rr = rsqrtf(t * (1.0f / 1024.0f) + EPS);
;                 u32x4 w;
; #pragma unroll
;                 for (int n = 0; n < 2; ++n) {
;                     const f32x4 gg = acc[ai][0][m][n] * rr + bg[n], uu = acc[ai][1][m][n] * rr + bu[n];
;                     const float h0 = fast_silu(gg.x) * uu.x, h1 = fast_silu(gg.y) * uu.y, h2 = fast_silu(gg.z) * uu.z, h3 = fast_silu(gg.w) * uu.w;
;                     w[2 * n] = cvt_pk_bf16(h0, h1); w[2 * n + 1] = cvt_pk_bf16(h2, h3);
;                 }
;                 bf16_t* hp = H + (size_t)row * DFF + u.pn * 128 + wc * 32 + fq * 8;
;                 if (cnt) asm volatile("global_store_dwordx4 %0, %1, off sc0 sc1" :: "v"(hp), "v"(w) : "memory");
;                 else *(u32x4*)hp = w;
;             }
.LBB0_238:
	v_or_b32_e32 v130, 16, v160
	v_ashrrev_i32_e32 v131, 31, v130
	v_mov_b64_e32 v[132:133], v[224:225]
	v_mov_b64_e32 v[134:135], v[226:227]
	v_mov_b32_e32 v136, v133
	v_mov_b32_e32 v137, v134
	v_mov_b32_e32 v133, v135
	v_pk_add_f32 v[132:133], v[136:137], v[132:133]
	s_nop 0
	v_add_f32_e32 v131, v132, v133
	ds_bpermute_b32 v132, v164, v131
	s_waitcnt lgkmcnt(0)
	v_add_f32_e32 v131, v131, v132
	ds_bpermute_b32 v132, v165, v131
	s_waitcnt lgkmcnt(0)
	v_add_f32_e32 v131, v131, v132
	v_fmamk_f32 v131, v131, 0x3a800000, v252
	v_cmp_gt_f32_e32 vcc, s49, v131
	v_mul_f32_e32 v132, 0x4b800000, v131
	s_nop 0
	v_cndmask_b32_e32 v131, v131, v132, vcc
	v_rsq_f32_e32 v131, v131
	s_nop 0
	v_mul_f32_e32 v132, 0x45800000, v131
	v_cndmask_b32_e32 v132, v131, v132, vcc
	v_pk_fma_f32 v[124:125], v[124:125], v[132:133], v[44:45] op_sel_hi:[1,0,1]
	v_pk_fma_f32 v[126:127], v[126:127], v[132:133], v[46:47] op_sel_hi:[1,0,1]
	v_mul_f32_e32 v131, 0xbfb8aa3b, v124
	v_exp_f32_e32 v131, v131
	v_pk_fma_f32 v[116:117], v[116:117], v[132:133], v[40:41] op_sel_hi:[1,0,1]
	v_pk_fma_f32 v[118:119], v[118:119], v[132:133], v[42:43] op_sel_hi:[1,0,1]
	v_pk_fma_f32 v[120:121], v[120:121], v[132:133], v[36:37] op_sel_hi:[1,0,1]
	v_add_f32_e32 v131, 1.0, v131
	v_rcp_f32_e32 v134, v131
	v_mul_f32_e32 v131, 0xbfb8aa3b, v125
	v_exp_f32_e32 v131, v131
	v_pk_fma_f32 v[112:113], v[112:113], v[132:133], v[32:33] op_sel_hi:[1,0,1]
	v_pk_fma_f32 v[114:115], v[114:115], v[132:133], v[34:35] op_sel_hi:[1,0,1]
	s_and_b64 vcc, exec, s[6:7]
	v_add_f32_e32 v131, 1.0, v131
	v_rcp_f32_e32 v135, v131
	s_nop 0
	v_pk_mul_f32 v[124:125], v[124:125], v[134:135]
	s_nop 0
	v_pk_mul_f32 v[116:117], v[116:117], v[124:125]
	v_mul_f32_e32 v124, 0xbfb8aa3b, v126
	v_mul_f32_e32 v125, 0xbfb8aa3b, v127
	v_exp_f32_e32 v124, v124
	v_exp_f32_e32 v125, v125
	v_cvt_pk_bf16_f32 v116, v116, v117
	v_add_f32_e32 v124, 1.0, v124
	v_add_f32_e32 v125, 1.0, v125
	v_rcp_f32_e32 v124, v124
	v_rcp_f32_e32 v125, v125
	s_nop 0
	v_pk_mul_f32 v[124:125], v[126:127], v[124:125]
	s_nop 0
	v_pk_mul_f32 v[118:119], v[118:119], v[124:125]
	s_nop 0
	v_cvt_pk_bf16_f32 v117, v118, v119
	v_pk_fma_f32 v[118:119], v[122:123], v[132:133], v[38:39] op_sel_hi:[1,0,1]
	v_mul_f32_e32 v122, 0xbfb8aa3b, v120
	v_mul_f32_e32 v123, 0xbfb8aa3b, v121
	v_exp_f32_e32 v122, v122
	v_exp_f32_e32 v123, v123
	v_add_f32_e32 v122, 1.0, v122
	v_add_f32_e32 v123, 1.0, v123
	v_rcp_f32_e32 v122, v122
	v_rcp_f32_e32 v123, v123
	s_nop 0
	v_pk_mul_f32 v[120:121], v[120:121], v[122:123]
	s_nop 0
	v_pk_mul_f32 v[112:113], v[112:113], v[120:121]
	v_mul_f32_e32 v120, 0xbfb8aa3b, v118
	v_mul_f32_e32 v121, 0xbfb8aa3b, v119
	v_exp_f32_e32 v120, v120
	v_exp_f32_e32 v121, v121
	v_add_f32_e32 v120, 1.0, v120
	v_add_f32_e32 v121, 1.0, v121
	v_rcp_f32_e32 v120, v120
	v_rcp_f32_e32 v121, v121
	s_nop 0
	v_pk_mul_f32 v[118:119], v[118:119], v[120:121]
	s_nop 0
	v_pk_mul_f32 v[114:115], v[114:115], v[118:119]
	v_cvt_pk_bf16_f32 v118, v112, v113
	v_mov_b64_e32 v[112:113], s[12:13]
	v_mad_i64_i32 v[112:113], s[20:21], v130, s1, v[112:113]
	v_lshl_add_u64 v[112:113], s[84:85], 1, v[112:113]
	v_lshl_add_u64 v[112:113], v[112:113], 0, s[52:53]
	v_cvt_pk_bf16_f32 v119, v114, v115
	v_lshl_add_u64 v[112:113], v[112:113], 0, v[128:129]
	s_cbranch_vccnz .LBB0_268
	global_store_dwordx4 v[112:113], v[116:119], off sc0 sc1
	s_cbranch_execnz .LBB0_241

; __device__ __forceinline__ unsigned cvt_pk_bf16(float lo, float hi) { const f32x2 v = {lo, hi}; return __builtin_bit_cast(unsigned, __builtin_convertvector(v, bf16x2_t)); }
; __device__ __forceinline__ float fast_silu(float g) { return g * __builtin_amdgcn_rcpf(1.0f + __builtin_amdgcn_exp2f(-1.4426950408889634f * g)); }
; __device__ __forceinline__ float sum4(f32x4 v) { return (v.x + v.y) + (v.z + v.w); }
; __device__ __forceinline__ float quad_sum(float t, int lane) { t += shx(t, 16, lane); t += shx(t, 32, lane); return t; }
;     template <int A0, int A1> __device__ __forceinline__ void run(const f32x4 (&acc)[2][2][4][2], const Unit& u, int wr, int wc, int fr, int fq) const {
;     ...
;             for (int m = 0; m < 4; ++m) {
;                 const int row = row0 + ai * 128 + m * 16;
;                 const float t = quad_sum(sum4(*(const f32x4*)(ssqp + (size_t)row * 16 + 4 * fq)), fq * 16 + fr);
;                 const float rr = rsqrtf(t * (1.0f / 1024.0f) + EPS);
;                 u32x4 w;
; #pragma unroll
;                 for (int n = 0; n < 2; ++n) {
;                     const f32x4 gg = acc[ai][0][m][n] * rr + bg[n], uu = acc[ai][1][m][n] * rr + bu[n];
;                     const float h0 = fast_silu(gg.x) * uu.x, h1 = fast_silu(gg.y) * uu.y, h2 = fast_silu(gg.z) * uu.z, h3 = fast_silu(gg.w) * uu.w;
;                     w[2 * n] = cvt_pk_bf16(h0, h1); w[2 * n + 1] = cvt_pk_bf16(h2, h3);
;                 }
;                 bf16_t* hp = H + (size_t)row * DFF + u.pn * 128 + wc * 32 + fq * 8;
;                 if (cnt) asm volatile("global_store_dwordx4 %0, %1, off sc0 sc1" :: "v"(hp), "v"(w) : "memory");
;                 else *(u32x4*)hp = w;
;             }
.LBB0_241:
	v_or_b32_e32 v112, 32, v160
	v_ashrrev_i32_e32 v113, 31, v112
	v_mov_b64_e32 v[114:115], v[228:229]
	v_mov_b64_e32 v[116:117], v[230:231]
	v_mov_b32_e32 v118, v115
	v_mov_b32_e32 v119, v116
	v_mov_b32_e32 v115, v117
	v_pk_add_f32 v[114:115], v[118:119], v[114:115]
	s_nop 0
	v_add_f32_e32 v113, v114, v115
	ds_bpermute_b32 v114, v164, v113
	s_waitcnt lgkmcnt(0)
	v_add_f32_e32 v113, v113, v114
	ds_bpermute_b32 v114, v165, v113
	s_waitcnt lgkmcnt(0)
	v_add_f32_e32 v113, v113, v114
	v_fmamk_f32 v113, v113, 0x3a800000, v252
	v_cmp_gt_f32_e32 vcc, s49, v113
	v_mul_f32_e32 v114, 0x4b800000, v113
	s_nop 0
	v_cndmask_b32_e32 v113, v113, v114, vcc
	v_rsq_f32_e32 v113, v113
	s_nop 0
	v_mul_f32_e32 v114, 0x45800000, v113
	v_cndmask_b32_e32 v114, v113, v114, vcc
	v_pk_fma_f32 v[108:109], v[108:109], v[114:115], v[44:45] op_sel_hi:[1,0,1]
	v_pk_fma_f32 v[110:111], v[110:111], v[114:115], v[46:47] op_sel_hi:[1,0,1]
	v_mul_f32_e32 v113, 0xbfb8aa3b, v108
	v_exp_f32_e32 v113, v113
	v_pk_fma_f32 v[100:101], v[100:101], v[114:115], v[40:41] op_sel_hi:[1,0,1]
	v_pk_fma_f32 v[102:103], v[102:103], v[114:115], v[42:43] op_sel_hi:[1,0,1]
	v_pk_fma_f32 v[104:105], v[104:105], v[114:115], v[36:37] op_sel_hi:[1,0,1]
	v_add_f32_e32 v113, 1.0, v113
	v_rcp_f32_e32 v116, v113
	v_mul_f32_e32 v113, 0xbfb8aa3b, v109
	v_exp_f32_e32 v113, v113
	v_pk_fma_f32 v[96:97], v[96:97], v[114:115], v[32:33] op_sel_hi:[1,0,1]
	v_pk_fma_f32 v[98:99], v[98:99], v[114:115], v[34:35] op_sel_hi:[1,0,1]
	s_and_b64 vcc, exec, s[6:7]
	v_add_f32_e32 v113, 1.0, v113
	v_rcp_f32_e32 v117, v113
	s_nop 0
	v_pk_mul_f32 v[108:109], v[108:109], v[116:117]
	s_nop 0
	v_pk_mul_f32 v[100:101], v[100:101], v[108:109]
	v_mul_f32_e32 v108, 0xbfb8aa3b, v110
	v_mul_f32_e32 v109, 0xbfb8aa3b, v111
	v_exp_f32_e32 v108, v108
	v_exp_f32_e32 v109, v109
	v_cvt_pk_bf16_f32 v100, v100, v101
	v_add_f32_e32 v108, 1.0, v108
	v_add_f32_e32 v109, 1.0, v109
	v_rcp_f32_e32 v108, v108
	v_rcp_f32_e32 v109, v109
	s_nop 0
	v_pk_mul_f32 v[108:109], v[110:111], v[108:109]
	s_nop 0
	v_pk_mul_f32 v[102:103], v[102:103], v[108:109]
	s_nop 0
	v_cvt_pk_bf16_f32 v101, v102, v103
	v_pk_fma_f32 v[102:103], v[106:107], v[114:115], v[38:39] op_sel_hi:[1,0,1]
	v_mul_f32_e32 v106, 0xbfb8aa3b, v104
	v_mul_f32_e32 v107, 0xbfb8aa3b, v105
	v_exp_f32_e32 v106, v106
	v_exp_f32_e32 v107, v107
	v_add_f32_e32 v106, 1.0, v106
	v_add_f32_e32 v107, 1.0, v107
	v_rcp_f32_e32 v106, v106
	v_rcp_f32_e32 v107, v107
	s_nop 0
	v_pk_mul_f32 v[104:105], v[104:105], v[106:107]
	s_nop 0
	v_pk_mul_f32 v[96:97], v[96:97], v[104:105]
	v_mul_f32_e32 v104, 0xbfb8aa3b, v102
	v_mul_f32_e32 v105, 0xbfb8aa3b, v103
	v_exp_f32_e32 v104, v104
	v_exp_f32_e32 v105, v105
	v_add_f32_e32 v104, 1.0, v104
	v_add_f32_e32 v105, 1.0, v105
	v_rcp_f32_e32 v104, v104
	v_rcp_f32_e32 v105, v105
	s_nop 0
	v_pk_mul_f32 v[102:103], v[102:103], v[104:105]
	s_nop 0
	v_pk_mul_f32 v[98:99], v[98:99], v[102:103]
	v_cvt_pk_bf16_f32 v102, v96, v97
	v_mov_b64_e32 v[96:97], s[12:13]
	v_mad_i64_i32 v[96:97], s[20:21], v112, s1, v[96:97]
	v_lshl_add_u64 v[96:97], s[84:85], 1, v[96:97]
	v_lshl_add_u64 v[96:97], v[96:97], 0, s[52:53]
	v_cvt_pk_bf16_f32 v103, v98, v99
	v_lshl_add_u64 v[96:97], v[96:97], 0, v[128:129]
	s_cbranch_vccnz .LBB0_269
	global_store_dwordx4 v[96:97], v[100:103], off sc0 sc1
	s_cbranch_execnz .LBB0_244

; __device__ __forceinline__ unsigned cvt_pk_bf16(float lo, float hi) { const f32x2 v = {lo, hi}; return __builtin_bit_cast(unsigned, __builtin_convertvector(v, bf16x2_t)); }
; __device__ __forceinline__ float fast_silu(float g) { return g * __builtin_amdgcn_rcpf(1.0f + __builtin_amdgcn_exp2f(-1.4426950408889634f * g)); }
; __device__ __forceinline__ float sum4(f32x4 v) { return (v.x + v.y) + (v.z + v.w); }
; __device__ __forceinline__ float quad_sum(float t, int lane) { t += shx(t, 16, lane); t += shx(t, 32, lane); return t; }
;     template <int A0, int A1> __device__ __forceinline__ void run(const f32x4 (&acc)[2][2][4][2], const Unit& u, int wr, int wc, int fr, int fq) const {
;     ...
;             for (int m = 0; m < 4; ++m) {
;                 const int row = row0 + ai * 128 + m * 16;
;                 const float t = quad_sum(sum4(*(const f32x4*)(ssqp + (size_t)row * 16 + 4 * fq)), fq * 16 + fr);
;                 const float rr = rsqrtf(t * (1.0f / 1024.0f) + EPS);
;                 u32x4 w;
; #pragma unroll
;                 for (int n = 0; n < 2; ++n) {
;                     const f32x4 gg = acc[ai][0][m][n] * rr + bg[n], uu = acc[ai][1][m][n] * rr + bu[n];
;                     const float h0 = fast_silu(gg.x) * uu.x, h1 = fast_silu(gg.y) * uu.y, h2 = fast_silu(gg.z) * uu.z, h3 = fast_silu(gg.w) * uu.w;
;                     w[2 * n] = cvt_pk_bf16(h0, h1); w[2 * n + 1] = cvt_pk_bf16(h2, h3);
;                 }
;                 bf16_t* hp = H + (size_t)row * DFF + u.pn * 128 + wc * 32 + fq * 8;
;                 if (cnt) asm volatile("global_store_dwordx4 %0, %1, off sc0 sc1" :: "v"(hp), "v"(w) : "memory");
;                 else *(u32x4*)hp = w;
;             }
.LBB0_244:
	v_or_b32_e32 v96, 48, v160
	v_ashrrev_i32_e32 v97, 31, v96
	v_mov_b64_e32 v[98:99], v[232:233]
	v_mov_b64_e32 v[100:101], v[234:235]
	v_mov_b32_e32 v102, v99
	v_mov_b32_e32 v103, v100
	v_mov_b32_e32 v99, v101
	v_pk_add_f32 v[98:99], v[102:103], v[98:99]
	s_nop 0
	v_add_f32_e32 v97, v98, v99
	ds_bpermute_b32 v98, v164, v97
	s_waitcnt lgkmcnt(0)
	v_add_f32_e32 v97, v97, v98
	ds_bpermute_b32 v98, v165, v97
	s_waitcnt lgkmcnt(0)
	v_add_f32_e32 v97, v97, v98
	v_fmamk_f32 v97, v97, 0x3a800000, v252
	v_cmp_gt_f32_e32 vcc, s49, v97
	v_mul_f32_e32 v98, 0x4b800000, v97
	s_nop 0
	v_cndmask_b32_e32 v97, v97, v98, vcc
	v_rsq_f32_e32 v97, v97
	s_nop 0
	v_mul_f32_e32 v98, 0x45800000, v97
	v_cndmask_b32_e32 v98, v97, v98, vcc
	v_pk_fma_f32 v[92:93], v[92:93], v[98:99], v[44:45] op_sel_hi:[1,0,1]
	v_pk_fma_f32 v[94:95], v[94:95], v[98:99], v[46:47] op_sel_hi:[1,0,1]
	v_mul_f32_e32 v97, 0xbfb8aa3b, v92
	v_exp_f32_e32 v97, v97
	v_pk_fma_f32 v[84:85], v[84:85], v[98:99], v[40:41] op_sel_hi:[1,0,1]
	v_pk_fma_f32 v[86:87], v[86:87], v[98:99], v[42:43] op_sel_hi:[1,0,1]
	v_pk_fma_f32 v[88:89], v[88:89], v[98:99], v[36:37] op_sel_hi:[1,0,1]
	v_add_f32_e32 v97, 1.0, v97
	v_rcp_f32_e32 v100, v97
	v_mul_f32_e32 v97, 0xbfb8aa3b, v93
	v_exp_f32_e32 v97, v97
	v_pk_fma_f32 v[80:81], v[80:81], v[98:99], v[32:33] op_sel_hi:[1,0,1]
	v_pk_fma_f32 v[82:83], v[82:83], v[98:99], v[34:35] op_sel_hi:[1,0,1]
	s_and_b64 vcc, exec, s[6:7]
	v_add_f32_e32 v97, 1.0, v97
	v_rcp_f32_e32 v101, v97
	s_nop 0
	v_pk_mul_f32 v[92:93], v[92:93], v[100:101]
	s_nop 0
	v_pk_mul_f32 v[84:85], v[84:85], v[92:93]
	v_mul_f32_e32 v92, 0xbfb8aa3b, v94
	v_mul_f32_e32 v93, 0xbfb8aa3b, v95
	v_exp_f32_e32 v92, v92
	v_exp_f32_e32 v93, v93
	v_cvt_pk_bf16_f32 v84, v84, v85
	v_add_f32_e32 v92, 1.0, v92
	v_add_f32_e32 v93, 1.0, v93
	v_rcp_f32_e32 v92, v92
	v_rcp_f32_e32 v93, v93
	s_nop 0
	v_pk_mul_f32 v[92:93], v[94:95], v[92:93]
	s_nop 0
	v_pk_mul_f32 v[86:87], v[86:87], v[92:93]
	s_nop 0
	v_cvt_pk_bf16_f32 v85, v86, v87
	v_pk_fma_f32 v[86:87], v[90:91], v[98:99], v[38:39] op_sel_hi:[1,0,1]
	v_mul_f32_e32 v90, 0xbfb8aa3b, v88
	v_mul_f32_e32 v91, 0xbfb8aa3b, v89
	v_exp_f32_e32 v90, v90
	v_exp_f32_e32 v91, v91
	v_add_f32_e32 v90, 1.0, v90
	v_add_f32_e32 v91, 1.0, v91
	v_rcp_f32_e32 v90, v90
	v_rcp_f32_e32 v91, v91
	s_nop 0
	v_pk_mul_f32 v[88:89], v[88:89], v[90:91]
	s_nop 0
	v_pk_mul_f32 v[80:81], v[80:81], v[88:89]
	v_mul_f32_e32 v88, 0xbfb8aa3b, v86
	v_mul_f32_e32 v89, 0xbfb8aa3b, v87
	v_exp_f32_e32 v88, v88
	v_exp_f32_e32 v89, v89
	v_add_f32_e32 v88, 1.0, v88
	v_add_f32_e32 v89, 1.0, v89
	v_rcp_f32_e32 v88, v88
	v_rcp_f32_e32 v89, v89
	s_nop 0
	v_pk_mul_f32 v[86:87], v[86:87], v[88:89]
	s_nop 0
	v_pk_mul_f32 v[82:83], v[82:83], v[86:87]
	v_cvt_pk_bf16_f32 v86, v80, v81
	v_mov_b64_e32 v[80:81], s[12:13]
	v_mad_i64_i32 v[80:81], s[20:21], v96, s1, v[80:81]
	v_lshl_add_u64 v[80:81], s[84:85], 1, v[80:81]
	v_lshl_add_u64 v[80:81], v[80:81], 0, s[52:53]
	v_cvt_pk_bf16_f32 v87, v82, v83
	v_lshl_add_u64 v[80:81], v[80:81], 0, v[128:129]
	s_cbranch_vccnz .LBB0_270
	global_store_dwordx4 v[80:81], v[84:87], off sc0 sc1
	s_cbranch_execnz .LBB0_247

; __device__ __forceinline__ unsigned cvt_pk_bf16(float lo, float hi) { const f32x2 v = {lo, hi}; return __builtin_bit_cast(unsigned, __builtin_convertvector(v, bf16x2_t)); }
; __device__ __forceinline__ float fast_silu(float g) { return g * __builtin_amdgcn_rcpf(1.0f + __builtin_amdgcn_exp2f(-1.4426950408889634f * g)); }
; __device__ __forceinline__ float sum4(f32x4 v) { return (v.x + v.y) + (v.z + v.w); }
; __device__ __forceinline__ float quad_sum(float t, int lane) { t += shx(t, 16, lane); t += shx(t, 32, lane); return t; }
;     template <int A0, int A1> __device__ __forceinline__ void run(const f32x4 (&acc)[2][2][4][2], const Unit& u, int wr, int wc, int fr, int fq) const {
;     ...
;             for (int m = 0; m < 4; ++m) {
;                 const int row = row0 + ai * 128 + m * 16;
;                 const float t = quad_sum(sum4(*(const f32x4*)(ssqp + (size_t)row * 16 + 4 * fq)), fq * 16 + fr);
;                 const float rr = rsqrtf(t * (1.0f / 1024.0f) + EPS);
;                 u32x4 w;
; #pragma unroll
;                 for (int n = 0; n < 2; ++n) {
;                     const f32x4 gg = acc[ai][0][m][n] * rr + bg[n], uu = acc[ai][1][m][n] * rr + bu[n];
;                     const float h0 = fast_silu(gg.x) * uu.x, h1 = fast_silu(gg.y) * uu.y, h2 = fast_silu(gg.z) * uu.z, h3 = fast_silu(gg.w) * uu.w;
;                     w[2 * n] = cvt_pk_bf16(h0, h1); w[2 * n + 1] = cvt_pk_bf16(h2, h3);
;                 }
;                 bf16_t* hp = H + (size_t)row * DFF + u.pn * 128 + wc * 32 + fq * 8;
;                 if (cnt) asm volatile("global_store_dwordx4 %0, %1, off sc0 sc1" :: "v"(hp), "v"(w) : "memory");
;                 else *(u32x4*)hp = w;
;             }
.LBB0_247:
	v_add_u32_e32 v80, 0x80, v160
	v_ashrrev_i32_e32 v81, 31, v80
	v_mov_b64_e32 v[82:83], v[240:241]
	v_mov_b64_e32 v[84:85], v[242:243]
	v_mov_b32_e32 v86, v83
	v_mov_b32_e32 v87, v84
	v_mov_b32_e32 v83, v85
	v_pk_add_f32 v[82:83], v[86:87], v[82:83]
	s_nop 0
	v_add_f32_e32 v81, v82, v83
	ds_bpermute_b32 v82, v164, v81
	s_waitcnt lgkmcnt(0)
	v_add_f32_e32 v81, v81, v82
	ds_bpermute_b32 v82, v165, v81
	s_waitcnt lgkmcnt(0)
	v_add_f32_e32 v81, v81, v82
	v_fmamk_f32 v81, v81, 0x3a800000, v252
	v_cmp_gt_f32_e32 vcc, s49, v81
	v_mul_f32_e32 v82, 0x4b800000, v81
	s_nop 0
	v_cndmask_b32_e32 v81, v81, v82, vcc
	v_rsq_f32_e32 v81, v81
	s_nop 0
	v_mul_f32_e32 v82, 0x45800000, v81
	v_cndmask_b32_e32 v82, v81, v82, vcc
	v_pk_fma_f32 v[76:77], v[76:77], v[82:83], v[44:45] op_sel_hi:[1,0,1]
	v_pk_fma_f32 v[78:79], v[78:79], v[82:83], v[46:47] op_sel_hi:[1,0,1]
	v_mul_f32_e32 v81, 0xbfb8aa3b, v76
	v_exp_f32_e32 v81, v81
	v_pk_fma_f32 v[68:69], v[68:69], v[82:83], v[40:41] op_sel_hi:[1,0,1]
	v_pk_fma_f32 v[70:71], v[70:71], v[82:83], v[42:43] op_sel_hi:[1,0,1]
	v_pk_fma_f32 v[72:73], v[72:73], v[82:83], v[36:37] op_sel_hi:[1,0,1]
	v_add_f32_e32 v81, 1.0, v81
	v_rcp_f32_e32 v84, v81
	v_mul_f32_e32 v81, 0xbfb8aa3b, v77
	v_exp_f32_e32 v81, v81
	v_pk_fma_f32 v[64:65], v[64:65], v[82:83], v[32:33] op_sel_hi:[1,0,1]
	v_pk_fma_f32 v[66:67], v[66:67], v[82:83], v[34:35] op_sel_hi:[1,0,1]
	s_and_b64 vcc, exec, s[6:7]
	v_add_f32_e32 v81, 1.0, v81
	v_rcp_f32_e32 v85, v81
	s_nop 0
	v_pk_mul_f32 v[76:77], v[76:77], v[84:85]
	s_nop 0
	v_pk_mul_f32 v[68:69], v[68:69], v[76:77]
	v_mul_f32_e32 v76, 0xbfb8aa3b, v78
	v_mul_f32_e32 v77, 0xbfb8aa3b, v79
	v_exp_f32_e32 v76, v76
	v_exp_f32_e32 v77, v77
	v_cvt_pk_bf16_f32 v68, v68, v69
	v_add_f32_e32 v76, 1.0, v76
	v_add_f32_e32 v77, 1.0, v77
	v_rcp_f32_e32 v76, v76
	v_rcp_f32_e32 v77, v77
	s_nop 0
	v_pk_mul_f32 v[76:77], v[78:79], v[76:77]
	s_nop 0
	v_pk_mul_f32 v[70:71], v[70:71], v[76:77]
	s_nop 0
	v_cvt_pk_bf16_f32 v69, v70, v71
	v_pk_fma_f32 v[70:71], v[74:75], v[82:83], v[38:39] op_sel_hi:[1,0,1]
	v_mul_f32_e32 v74, 0xbfb8aa3b, v72
	v_mul_f32_e32 v75, 0xbfb8aa3b, v73
	v_exp_f32_e32 v74, v74
	v_exp_f32_e32 v75, v75
	v_add_f32_e32 v74, 1.0, v74
	v_add_f32_e32 v75, 1.0, v75
	v_rcp_f32_e32 v74, v74
	v_rcp_f32_e32 v75, v75
	s_nop 0
	v_pk_mul_f32 v[72:73], v[72:73], v[74:75]
	s_nop 0
	v_pk_mul_f32 v[64:65], v[64:65], v[72:73]
	v_mul_f32_e32 v72, 0xbfb8aa3b, v70
	v_mul_f32_e32 v73, 0xbfb8aa3b, v71
	v_exp_f32_e32 v72, v72
	v_exp_f32_e32 v73, v73
	v_add_f32_e32 v72, 1.0, v72
	v_add_f32_e32 v73, 1.0, v73
	v_rcp_f32_e32 v72, v72
	v_rcp_f32_e32 v73, v73
	s_nop 0
	v_pk_mul_f32 v[70:71], v[70:71], v[72:73]
	s_nop 0
	v_pk_mul_f32 v[66:67], v[66:67], v[70:71]
	v_cvt_pk_bf16_f32 v70, v64, v65
	v_mov_b64_e32 v[64:65], s[12:13]
	v_mad_i64_i32 v[64:65], s[20:21], v80, s1, v[64:65]
	v_lshl_add_u64 v[64:65], s[84:85], 1, v[64:65]
	v_lshl_add_u64 v[64:65], v[64:65], 0, s[52:53]
	v_cvt_pk_bf16_f32 v71, v66, v67
	v_lshl_add_u64 v[64:65], v[64:65], 0, v[128:129]
	s_cbranch_vccnz .LBB0_271
	global_store_dwordx4 v[64:65], v[68:71], off sc0 sc1
	s_cbranch_execnz .LBB0_250

; __device__ __forceinline__ unsigned cvt_pk_bf16(float lo, float hi) { const f32x2 v = {lo, hi}; return __builtin_bit_cast(unsigned, __builtin_convertvector(v, bf16x2_t)); }
; __device__ __forceinline__ float fast_silu(float g) { return g * __builtin_amdgcn_rcpf(1.0f + __builtin_amdgcn_exp2f(-1.4426950408889634f * g)); }
; __device__ __forceinline__ float sum4(f32x4 v) { return (v.x + v.y) + (v.z + v.w); }
; __device__ __forceinline__ float quad_sum(float t, int lane) { t += shx(t, 16, lane); t += shx(t, 32, lane); return t; }
;     template <int A0, int A1> __device__ __forceinline__ void run(const f32x4 (&acc)[2][2][4][2], const Unit& u, int wr, int wc, int fr, int fq) const {
;     ...
;             for (int m = 0; m < 4; ++m) {
;                 const int row = row0 + ai * 128 + m * 16;
;                 const float t = quad_sum(sum4(*(const f32x4*)(ssqp + (size_t)row * 16 + 4 * fq)), fq * 16 + fr);
;                 const float rr = rsqrtf(t * (1.0f / 1024.0f) + EPS);
;                 u32x4 w;
; #pragma unroll
;                 for (int n = 0; n < 2; ++n) {
;                     const f32x4 gg = acc[ai][0][m][n] * rr + bg[n], uu = acc[ai][1][m][n] * rr + bu[n];
;                     const float h0 = fast_silu(gg.x) * uu.x, h1 = fast_silu(gg.y) * uu.y, h2 = fast_silu(gg.z) * uu.z, h3 = fast_silu(gg.w) * uu.w;
;                     w[2 * n] = cvt_pk_bf16(h0, h1); w[2 * n + 1] = cvt_pk_bf16(h2, h3);
;                 }
;                 bf16_t* hp = H + (size_t)row * DFF + u.pn * 128 + wc * 32 + fq * 8;
;                 if (cnt) asm volatile("global_store_dwordx4 %0, %1, off sc0 sc1" :: "v"(hp), "v"(w) : "memory");
;                 else *(u32x4*)hp = w;
;             }
.LBB0_250:
	v_add_u32_e32 v64, 0x90, v160
	v_ashrrev_i32_e32 v65, 31, v64
	v_mov_b64_e32 v[66:67], v[244:245]
	v_mov_b64_e32 v[68:69], v[246:247]
	v_mov_b32_e32 v70, v67
	v_mov_b32_e32 v71, v68
	v_mov_b32_e32 v67, v69
	v_pk_add_f32 v[66:67], v[70:71], v[66:67]
	s_nop 0
	v_add_f32_e32 v65, v66, v67
	ds_bpermute_b32 v66, v164, v65
	s_waitcnt lgkmcnt(0)
	v_add_f32_e32 v65, v65, v66
	ds_bpermute_b32 v66, v165, v65
	s_waitcnt lgkmcnt(0)
	v_add_f32_e32 v65, v65, v66
	v_fmamk_f32 v65, v65, 0x3a800000, v252
	v_cmp_gt_f32_e32 vcc, s49, v65
	v_mul_f32_e32 v66, 0x4b800000, v65
	s_nop 0
	v_cndmask_b32_e32 v65, v65, v66, vcc
	v_rsq_f32_e32 v65, v65
	s_nop 0
	v_mul_f32_e32 v66, 0x45800000, v65
	v_cndmask_b32_e32 v66, v65, v66, vcc
	v_pk_fma_f32 v[60:61], v[60:61], v[66:67], v[44:45] op_sel_hi:[1,0,1]
	v_pk_fma_f32 v[62:63], v[62:63], v[66:67], v[46:47] op_sel_hi:[1,0,1]
	v_mul_f32_e32 v65, 0xbfb8aa3b, v60
	v_exp_f32_e32 v65, v65
	v_pk_fma_f32 v[52:53], v[52:53], v[66:67], v[40:41] op_sel_hi:[1,0,1]
	v_pk_fma_f32 v[54:55], v[54:55], v[66:67], v[42:43] op_sel_hi:[1,0,1]
	v_pk_fma_f32 v[56:57], v[56:57], v[66:67], v[36:37] op_sel_hi:[1,0,1]
	v_add_f32_e32 v65, 1.0, v65
	v_rcp_f32_e32 v68, v65
	v_mul_f32_e32 v65, 0xbfb8aa3b, v61
	v_exp_f32_e32 v65, v65
	v_pk_fma_f32 v[48:49], v[48:49], v[66:67], v[32:33] op_sel_hi:[1,0,1]
	v_pk_fma_f32 v[50:51], v[50:51], v[66:67], v[34:35] op_sel_hi:[1,0,1]
	s_and_b64 vcc, exec, s[6:7]
	v_add_f32_e32 v65, 1.0, v65
	v_rcp_f32_e32 v69, v65
	s_nop 0
	v_pk_mul_f32 v[60:61], v[60:61], v[68:69]
	s_nop 0
	v_pk_mul_f32 v[52:53], v[52:53], v[60:61]
	v_mul_f32_e32 v60, 0xbfb8aa3b, v62
	v_mul_f32_e32 v61, 0xbfb8aa3b, v63
	v_exp_f32_e32 v60, v60
	v_exp_f32_e32 v61, v61
	v_cvt_pk_bf16_f32 v52, v52, v53
	v_add_f32_e32 v60, 1.0, v60
	v_add_f32_e32 v61, 1.0, v61
	v_rcp_f32_e32 v60, v60
	v_rcp_f32_e32 v61, v61
	s_nop 0
	v_pk_mul_f32 v[60:61], v[62:63], v[60:61]
	s_nop 0
	v_pk_mul_f32 v[54:55], v[54:55], v[60:61]
	s_nop 0
	v_cvt_pk_bf16_f32 v53, v54, v55
	v_pk_fma_f32 v[54:55], v[58:59], v[66:67], v[38:39] op_sel_hi:[1,0,1]
	v_mul_f32_e32 v58, 0xbfb8aa3b, v56
	v_mul_f32_e32 v59, 0xbfb8aa3b, v57
	v_exp_f32_e32 v58, v58
	v_exp_f32_e32 v59, v59
	v_add_f32_e32 v58, 1.0, v58
	v_add_f32_e32 v59, 1.0, v59
	v_rcp_f32_e32 v58, v58
	v_rcp_f32_e32 v59, v59
	s_nop 0
	v_pk_mul_f32 v[56:57], v[56:57], v[58:59]
	s_nop 0
	v_pk_mul_f32 v[48:49], v[48:49], v[56:57]
	v_mul_f32_e32 v56, 0xbfb8aa3b, v54
	v_mul_f32_e32 v57, 0xbfb8aa3b, v55
	v_exp_f32_e32 v56, v56
	v_exp_f32_e32 v57, v57
	v_add_f32_e32 v56, 1.0, v56
	v_add_f32_e32 v57, 1.0, v57
	v_rcp_f32_e32 v56, v56
	v_rcp_f32_e32 v57, v57
	s_nop 0
	v_pk_mul_f32 v[54:55], v[54:55], v[56:57]
	s_nop 0
	v_pk_mul_f32 v[50:51], v[50:51], v[54:55]
	v_cvt_pk_bf16_f32 v54, v48, v49
	v_mov_b64_e32 v[48:49], s[12:13]
	v_mad_i64_i32 v[48:49], s[20:21], v64, s1, v[48:49]
	v_lshl_add_u64 v[48:49], s[84:85], 1, v[48:49]
	v_lshl_add_u64 v[48:49], v[48:49], 0, s[52:53]
	v_cvt_pk_bf16_f32 v55, v50, v51
	v_lshl_add_u64 v[48:49], v[48:49], 0, v[128:129]
	s_cbranch_vccnz .LBB0_272
	global_store_dwordx4 v[48:49], v[52:55], off sc0 sc1
	s_cbranch_execnz .LBB0_253

; __device__ __forceinline__ unsigned cvt_pk_bf16(float lo, float hi) { const f32x2 v = {lo, hi}; return __builtin_bit_cast(unsigned, __builtin_convertvector(v, bf16x2_t)); }
; __device__ __forceinline__ float fast_silu(float g) { return g * __builtin_amdgcn_rcpf(1.0f + __builtin_amdgcn_exp2f(-1.4426950408889634f * g)); }
; __device__ __forceinline__ float sum4(f32x4 v) { return (v.x + v.y) + (v.z + v.w); }
; __device__ __forceinline__ float quad_sum(float t, int lane) { t += shx(t, 16, lane); t += shx(t, 32, lane); return t; }
;     template <int A0, int A1> __device__ __forceinline__ void run(const f32x4 (&acc)[2][2][4][2], const Unit& u, int wr, int wc, int fr, int fq) const {
;     ...
;             for (int m = 0; m < 4; ++m) {
;                 const int row = row0 + ai * 128 + m * 16;
;                 const float t = quad_sum(sum4(*(const f32x4*)(ssqp + (size_t)row * 16 + 4 * fq)), fq * 16 + fr);
;                 const float rr = rsqrtf(t * (1.0f / 1024.0f) + EPS);
;                 u32x4 w;
; #pragma unroll
;                 for (int n = 0; n < 2; ++n) {
;                     const f32x4 gg = acc[ai][0][m][n] * rr + bg[n], uu = acc[ai][1][m][n] * rr + bu[n];
;                     const float h0 = fast_silu(gg.x) * uu.x, h1 = fast_silu(gg.y) * uu.y, h2 = fast_silu(gg.z) * uu.z, h3 = fast_silu(gg.w) * uu.w;
;                     w[2 * n] = cvt_pk_bf16(h0, h1); w[2 * n + 1] = cvt_pk_bf16(h2, h3);
;                 }
;                 bf16_t* hp = H + (size_t)row * DFF + u.pn * 128 + wc * 32 + fq * 8;
;                 if (cnt) asm volatile("global_store_dwordx4 %0, %1, off sc0 sc1" :: "v"(hp), "v"(w) : "memory");
;                 else *(u32x4*)hp = w;
;             }
.LBB0_253:
	v_add_u32_e32 v48, 0xa0, v160
	v_ashrrev_i32_e32 v49, 31, v48
	v_mov_b64_e32 v[50:51], v[248:249]
	v_mov_b64_e32 v[52:53], v[250:251]
	v_mov_b32_e32 v54, v51
	v_mov_b32_e32 v55, v52
	v_mov_b32_e32 v51, v53
	v_pk_add_f32 v[50:51], v[54:55], v[50:51]
	s_nop 0
	v_add_f32_e32 v49, v50, v51
	ds_bpermute_b32 v50, v164, v49
	s_waitcnt lgkmcnt(0)
	v_add_f32_e32 v49, v49, v50
	ds_bpermute_b32 v50, v165, v49
	s_waitcnt lgkmcnt(0)
	v_add_f32_e32 v49, v49, v50
	v_fmamk_f32 v49, v49, 0x3a800000, v252
	v_cmp_gt_f32_e32 vcc, s49, v49
	v_mul_f32_e32 v50, 0x4b800000, v49
	s_nop 0
	v_cndmask_b32_e32 v49, v49, v50, vcc
	v_rsq_f32_e32 v49, v49
	s_nop 0
	v_mul_f32_e32 v50, 0x45800000, v49
	v_cndmask_b32_e32 v50, v49, v50, vcc
	v_pk_fma_f32 v[28:29], v[28:29], v[50:51], v[44:45] op_sel_hi:[1,0,1]
	v_pk_fma_f32 v[30:31], v[30:31], v[50:51], v[46:47] op_sel_hi:[1,0,1]
	v_mul_f32_e32 v49, 0xbfb8aa3b, v28
	v_exp_f32_e32 v49, v49
	v_pk_fma_f32 v[20:21], v[20:21], v[50:51], v[40:41] op_sel_hi:[1,0,1]
	v_pk_fma_f32 v[22:23], v[22:23], v[50:51], v[42:43] op_sel_hi:[1,0,1]
	v_pk_fma_f32 v[24:25], v[24:25], v[50:51], v[36:37] op_sel_hi:[1,0,1]
	v_add_f32_e32 v49, 1.0, v49
	v_rcp_f32_e32 v52, v49
	v_mul_f32_e32 v49, 0xbfb8aa3b, v29
	v_exp_f32_e32 v49, v49
	v_pk_fma_f32 v[16:17], v[16:17], v[50:51], v[32:33] op_sel_hi:[1,0,1]
	v_pk_fma_f32 v[18:19], v[18:19], v[50:51], v[34:35] op_sel_hi:[1,0,1]
	s_and_b64 vcc, exec, s[6:7]
	v_add_f32_e32 v49, 1.0, v49
	v_rcp_f32_e32 v53, v49
	s_nop 0
	v_pk_mul_f32 v[28:29], v[28:29], v[52:53]
	s_nop 0
	v_pk_mul_f32 v[20:21], v[20:21], v[28:29]
	v_mul_f32_e32 v28, 0xbfb8aa3b, v30
	v_mul_f32_e32 v29, 0xbfb8aa3b, v31
	v_exp_f32_e32 v28, v28
	v_exp_f32_e32 v29, v29
	v_cvt_pk_bf16_f32 v20, v20, v21
	v_add_f32_e32 v28, 1.0, v28
	v_add_f32_e32 v29, 1.0, v29
	v_rcp_f32_e32 v28, v28
	v_rcp_f32_e32 v29, v29
	s_nop 0
	v_pk_mul_f32 v[28:29], v[30:31], v[28:29]
	s_nop 0
	v_pk_mul_f32 v[22:23], v[22:23], v[28:29]
	s_nop 0
	v_cvt_pk_bf16_f32 v21, v22, v23
	v_pk_fma_f32 v[22:23], v[26:27], v[50:51], v[38:39] op_sel_hi:[1,0,1]
	v_mul_f32_e32 v26, 0xbfb8aa3b, v24
	v_mul_f32_e32 v27, 0xbfb8aa3b, v25
	v_exp_f32_e32 v26, v26
	v_exp_f32_e32 v27, v27
	v_add_f32_e32 v26, 1.0, v26
	v_add_f32_e32 v27, 1.0, v27
	v_rcp_f32_e32 v26, v26
	v_rcp_f32_e32 v27, v27
	s_nop 0
	v_pk_mul_f32 v[24:25], v[24:25], v[26:27]
	s_nop 0
	v_pk_mul_f32 v[16:17], v[16:17], v[24:25]
	v_mul_f32_e32 v24, 0xbfb8aa3b, v22
	v_mul_f32_e32 v25, 0xbfb8aa3b, v23
	v_exp_f32_e32 v24, v24
	v_exp_f32_e32 v25, v25
	v_add_f32_e32 v24, 1.0, v24
	v_add_f32_e32 v25, 1.0, v25
	v_rcp_f32_e32 v24, v24
	v_rcp_f32_e32 v25, v25
	s_nop 0
	v_pk_mul_f32 v[22:23], v[22:23], v[24:25]
	s_nop 0
	v_pk_mul_f32 v[18:19], v[18:19], v[22:23]
	v_cvt_pk_bf16_f32 v22, v16, v17
	v_mov_b64_e32 v[16:17], s[12:13]
	v_mad_i64_i32 v[16:17], s[20:21], v48, s1, v[16:17]
	v_lshl_add_u64 v[16:17], s[84:85], 1, v[16:17]
	v_lshl_add_u64 v[16:17], v[16:17], 0, s[52:53]
	v_cvt_pk_bf16_f32 v23, v18, v19
	v_lshl_add_u64 v[16:17], v[16:17], 0, v[128:129]
	s_cbranch_vccnz .LBB0_273
	global_store_dwordx4 v[16:17], v[20:23], off sc0 sc1
	s_cbranch_execnz .LBB0_256
